# B item epilogue issues all sub-LN gain loads at once; residual epilogue (instance 3) loads above align barrier too
# baseline (speedup 1.0000x reference)
; #define DRAIN_DMA() asm volatile("s_waitcnt vmcnt(0)" ::: "memory")
; __device__ __forceinline__ void blk_B(int b, int hd, int chunk, const bf16_t* QK, const bf16_t* VT, bf16_t* mixed, LAS unsigned char* lds, const float* tblg, float wfar, float lam, float osc, const float* subln, int tid, int lane, int wave) {
;     ...
;     DRAIN_DMA();
;     la += __shfl_xor(la, 32); lb += __shfl_xor(lb, 32);
;     const float ia = 1.0f / la, ib = lam / lb;
;     float sq = 0.f;
; #pragma unroll
;     for (int i = 0; i < 16; ++i) { oa0[i] = oa0[i] * ia - ob0[i] * ib; oa1[i] = oa1[i] * ia - ob1[i] * ib; sq += oa0[i] * oa0[i] + oa1[i] * oa1[i]; }
;     sq += __shfl_xor(sq, 32);
;     const float rn = __builtin_amdgcn_rsqf(sq * (1.0f / 64.0f) + EPS) * osc;
;     ...
;     for (int c = 0; c < 4; ++c) { const f32x4 g0 = *(const f32x4*)(subln + 8 * c + 4 * h), g1 = *(const f32x4*)(subln + 32 + 8 * c + 4 * h);
.LBB0_308:
	v_and_b32_e32 v66, 64, v236
	v_xor_b32_e32 v0, 32, v236
	v_add_u32_e32 v66, 64, v66
	v_cmp_lt_i32_e32 vcc, v0, v66
	s_waitcnt vmcnt(0)
	s_lshl_b32 s92, s28, 1
	s_nop 0
	v_cndmask_b32_e32 v0, v236, v0, vcc
	v_lshlrev_b32_e32 v73, 2, v0
	ds_bpermute_b32 v66, v73, v200
	ds_bpermute_b32 v67, v73, v201
	s_waitcnt lgkmcnt(0)
	v_pk_add_f32 v[66:67], v[200:201], v[66:67]
	s_nop 0
	v_div_scale_f32 v0, s[0:1], v67, v67, s24
	v_rcp_f32_e32 v68, v0
	s_nop 0
	v_fma_f32 v69, -v0, v68, 1.0
	v_fmac_f32_e32 v68, v69, v68
	v_div_scale_f32 v69, vcc, s24, v67, s24
	v_mul_f32_e32 v70, v69, v68
	v_fma_f32 v71, -v0, v70, v69
	v_fmac_f32_e32 v70, v71, v68
	v_fma_f32 v0, -v0, v70, v69
	v_div_fmas_f32 v0, v0, v68, v70
	v_div_fixup_f32 v69, v0, v67, s24
	v_div_scale_f32 v0, s[0:1], v66, v66, 1.0
	v_rcp_f32_e32 v67, v0
	v_mov_b32_e32 v72, v69
	v_pk_mul_f32 v[60:61], v[60:61], v[72:73] op_sel_hi:[1,0]
	v_pk_mul_f32 v[34:35], v[34:35], v[72:73] op_sel_hi:[1,0]
	v_fma_f32 v68, -v0, v67, 1.0
	v_fmac_f32_e32 v67, v68, v67
	v_div_scale_f32 v68, vcc, 1.0, v66, 1.0
	v_mul_f32_e32 v70, v68, v67
	v_fma_f32 v71, -v0, v70, v68
	v_fmac_f32_e32 v70, v71, v67
	v_fma_f32 v0, -v0, v70, v68
	v_div_fmas_f32 v0, v0, v67, v70
	v_div_fixup_f32 v68, v0, v66, 1.0
	v_pk_fma_f32 v[66:67], v[12:13], v[68:69], v[60:61] op_sel_hi:[1,0,1] neg_lo:[0,0,1] neg_hi:[0,0,1]
	v_pk_mul_f32 v[12:13], v[44:45], v[72:73] op_sel_hi:[1,0]
	v_pk_mul_f32 v[36:37], v[36:37], v[72:73] op_sel_hi:[1,0]
	v_pk_fma_f32 v[60:61], v[28:29], v[68:69], v[12:13] op_sel_hi:[1,0,1] neg_lo:[0,0,1] neg_hi:[0,0,1]
	v_pk_fma_f32 v[18:19], v[18:19], v[68:69], v[34:35] op_sel_hi:[1,0,1] neg_lo:[0,0,1] neg_hi:[0,0,1]
	v_pk_mul_f32 v[12:13], v[60:61], v[60:61]
	v_pk_fma_f32 v[20:21], v[20:21], v[68:69], v[36:37] op_sel_hi:[1,0,1] neg_lo:[0,0,1] neg_hi:[0,0,1]
	v_pk_fma_f32 v[70:71], v[66:67], v[66:67], v[12:13]
	v_pk_mul_f32 v[12:13], v[62:63], v[72:73] op_sel_hi:[1,0]
	v_pk_mul_f32 v[34:35], v[18:19], v[18:19]
	v_pk_fma_f32 v[44:45], v[14:15], v[68:69], v[12:13] op_sel_hi:[1,0,1] neg_lo:[0,0,1] neg_hi:[0,0,1]
	v_pk_mul_f32 v[12:13], v[46:47], v[72:73] op_sel_hi:[1,0]
	v_mul_f32_e32 v14, v48, v69
	v_pk_fma_f32 v[28:29], v[30:31], v[68:69], v[12:13] op_sel_hi:[1,0,1] neg_lo:[0,0,1] neg_hi:[0,0,1]
	v_mov_b32_e32 v48, v33
	v_pk_mul_f32 v[12:13], v[28:29], v[28:29]
	v_pk_mul_f32 v[30:31], v[48:49], v[68:69]
	v_pk_fma_f32 v[46:47], v[44:45], v[44:45], v[12:13]
	v_mul_f32_e32 v12, v32, v68
	v_pk_mul_f32 v[32:33], v[64:65], v[72:73] op_sel_hi:[1,0]
	global_load_dwordx4 v[62:65], v[188:189], off
	global_load_dwordx4 v[74:77], v[188:189], off offset:128
	global_load_dwordx4 v[98:101], v[188:189], off offset:32
	global_load_dwordx4 v[102:105], v[188:189], off offset:160
	global_load_dwordx4 v[106:109], v[188:189], off offset:64
	global_load_dwordx4 v[110:113], v[188:189], off offset:192
	global_load_dwordx4 v[114:117], v[188:189], off offset:96
	global_load_dwordx4 v[118:121], v[188:189], off offset:224
	v_mov_b32_e32 v13, v30
	v_mov_b32_e32 v15, v31
	v_pk_add_f32 v[14:15], v[12:13], v[14:15] neg_lo:[0,1] neg_hi:[0,1]
	v_pk_mul_f32 v[48:49], v[52:53], v[72:73] op_sel_hi:[1,0]
	v_pk_fma_f32 v[16:17], v[16:17], v[68:69], v[32:33] op_sel_hi:[1,0,1] neg_lo:[0,0,1] neg_hi:[0,0,1]
	v_pk_mul_f32 v[12:13], v[14:15], v[14:15]
	v_pk_fma_f32 v[4:5], v[4:5], v[68:69], v[48:49] op_sel_hi:[1,0,1] neg_lo:[0,0,1] neg_hi:[0,0,1]
	v_pk_mul_f32 v[48:49], v[50:51], v[72:73] op_sel_hi:[1,0]
	v_pk_fma_f32 v[32:33], v[16:17], v[16:17], v[12:13]
	v_lshlrev_b64 v[12:13], 11, v[194:195]
	v_pk_fma_f32 v[2:3], v[2:3], v[68:69], v[48:49] op_sel_hi:[1,0,1] neg_lo:[0,0,1] neg_hi:[0,0,1]
	v_pk_mul_f32 v[48:49], v[56:57], v[72:73] op_sel_hi:[1,0]
	v_lshl_add_u64 v[12:13], s[98:99], 0, v[12:13]
	v_pk_fma_f32 v[48:49], v[8:9], v[68:69], v[48:49] op_sel_hi:[1,0,1] neg_lo:[0,0,1] neg_hi:[0,0,1]
	v_pk_mul_f32 v[8:9], v[54:55], v[72:73] op_sel_hi:[1,0]
	v_lshl_add_u64 v[12:13], v[12:13], 0, s[92:93]
	v_lshlrev_b32_e32 v0, 1, v178
	v_pk_mul_f32 v[36:37], v[20:21], v[20:21]
	v_pk_fma_f32 v[34:35], v[2:3], v[2:3], v[34:35]
	v_pk_fma_f32 v[50:51], v[6:7], v[68:69], v[8:9] op_sel_hi:[1,0,1] neg_lo:[0,0,1] neg_hi:[0,0,1]
	v_pk_mul_f32 v[8:9], v[38:39], v[72:73] op_sel_hi:[1,0]
	v_lshl_add_u64 v[30:31], v[12:13], 0, v[0:1]
	v_pk_fma_f32 v[36:37], v[4:5], v[4:5], v[36:37]
	v_pk_fma_f32 v[22:23], v[22:23], v[68:69], v[8:9] op_sel_hi:[1,0,1] neg_lo:[0,0,1] neg_hi:[0,0,1]
	v_add_f32_e32 v0, v34, v35
	v_pk_mul_f32 v[6:7], v[40:41], v[72:73] op_sel_hi:[1,0]
	v_pk_mul_f32 v[8:9], v[22:23], v[22:23]
	v_add_f32_e32 v0, v36, v0
	v_pk_fma_f32 v[24:25], v[24:25], v[68:69], v[6:7] op_sel_hi:[1,0,1] neg_lo:[0,0,1] neg_hi:[0,0,1]
	v_pk_fma_f32 v[8:9], v[50:51], v[50:51], v[8:9]
	v_pk_mul_f32 v[38:39], v[58:59], v[72:73] op_sel_hi:[1,0]
	v_add_f32_e32 v0, v37, v0
	v_pk_mul_f32 v[6:7], v[24:25], v[24:25]
	v_pk_fma_f32 v[10:11], v[10:11], v[68:69], v[38:39] op_sel_hi:[1,0,1] neg_lo:[0,0,1] neg_hi:[0,0,1]
	v_pk_mul_f32 v[38:39], v[42:43], v[72:73] op_sel_hi:[1,0]
	v_add_f32_e32 v0, v8, v0
	v_pk_fma_f32 v[6:7], v[48:49], v[48:49], v[6:7]
	v_pk_fma_f32 v[26:27], v[26:27], v[68:69], v[38:39] op_sel_hi:[1,0,1] neg_lo:[0,0,1] neg_hi:[0,0,1]
	v_add_f32_e32 v0, v9, v0
	v_pk_mul_f32 v[38:39], v[26:27], v[26:27]
	v_add_f32_e32 v0, v6, v0
	v_pk_fma_f32 v[38:39], v[10:11], v[10:11], v[38:39]
	v_add_f32_e32 v0, v7, v0
	v_add_f32_e32 v0, v38, v0
	v_add_f32_e32 v0, v39, v0
	v_add_f32_e32 v0, v70, v0
	v_add_f32_e32 v0, v71, v0
	v_add_f32_e32 v0, v46, v0
	v_add_f32_e32 v0, v47, v0
	v_add_f32_e32 v0, v32, v0
	v_add_f32_e32 v0, v33, v0
	ds_bpermute_b32 v6, v73, v0
	s_mov_b64 s[0:1], 0x440
	v_lshl_add_u64 v[12:13], v[30:31], 0, s[0:1]
	s_waitcnt lgkmcnt(0)
; __device__ __forceinline__ unsigned pkbf(float lo, float hi) { const f32x2_t v = {lo, hi}; const bf16x2_t b = __builtin_convertvector(v, bf16x2_t); return __builtin_bit_cast(unsigned, b); }
; __device__ __forceinline__ void blk_B(int b, int hd, int chunk, const bf16_t* QK, const bf16_t* VT, bf16_t* mixed, LAS unsigned char* lds, const float* tblg, float wfar, float lam, float osc, const float* subln, int tid, int lane, int wave) {
;     ...
;     const float rn = __builtin_amdgcn_rsqf(sq * (1.0f / 64.0f) + EPS) * osc;
;     bf16_t* op = mixed + (tok0 + qb * 32 + q) * DM + 512 + hd * 64;
; #pragma unroll
;     for (int c = 0; c < 4; ++c) { const f32x4 g0 = *(const f32x4*)(subln + 8 * c + 4 * h), g1 = *(const f32x4*)(subln + 32 + 8 * c + 4 * h);
;         u32x2 w; w.x = pkbf(oa0[4 * c] * rn * g0[0], oa0[4 * c + 1] * rn * g0[1]); w.y = pkbf(oa0[4 * c + 2] * rn * g0[2], oa0[4 * c + 3] * rn * g0[3]); *(u32x2*)(op + 8 * c + 4 * h) = w;
;         w.x = pkbf(oa1[4 * c] * rn * g1[0], oa1[4 * c + 1] * rn * g1[1]); w.y = pkbf(oa1[4 * c + 2] * rn * g1[2], oa1[4 * c + 3] * rn * g1[3]); *(u32x2*)(op + 32 + 8 * c + 4 * h) = w; }
	v_add_f32_e32 v0, v0, v6
	v_fmamk_f32 v0, v0, 0x3c800000, v229
	v_rsq_f32_e32 v0, v0
	s_nop 0
	v_mul_f32_e32 v0, v175, v0
	v_pk_mul_f32 v[2:3], v[2:3], v[0:1] op_sel_hi:[1,0]
	v_pk_mul_f32 v[4:5], v[4:5], v[0:1] op_sel_hi:[1,0]
	v_pk_mul_f32 v[10:11], v[10:11], v[0:1] op_sel_hi:[1,0]
	s_waitcnt vmcnt(0)
	v_pk_mul_f32 v[2:3], v[62:63], v[2:3]
	v_pk_mul_f32 v[4:5], v[64:65], v[4:5]
	v_cvt_pk_bf16_f32 v2, v2, v3
	v_cvt_pk_bf16_f32 v3, v4, v5
	global_store_dwordx2 v[30:31], v[2:3], off offset:1024
	v_pk_mul_f32 v[2:3], v[18:19], v[0:1] op_sel_hi:[1,0]
	v_pk_mul_f32 v[4:5], v[20:21], v[0:1] op_sel_hi:[1,0]
	v_pk_mul_f32 v[2:3], v[74:75], v[2:3]
	v_pk_mul_f32 v[4:5], v[76:77], v[4:5]
	v_cvt_pk_bf16_f32 v2, v2, v3
	v_cvt_pk_bf16_f32 v3, v4, v5
	global_store_dwordx2 v[30:31], v[2:3], off offset:1088
	v_pk_mul_f32 v[18:19], v[50:51], v[0:1] op_sel_hi:[1,0]
	s_nop 0
	v_pk_mul_f32 v[2:3], v[98:99], v[18:19]
	v_pk_mul_f32 v[18:19], v[48:49], v[0:1] op_sel_hi:[1,0]
	v_cvt_pk_bf16_f32 v2, v2, v3
	v_pk_mul_f32 v[4:5], v[100:101], v[18:19]
	s_nop 0
	v_cvt_pk_bf16_f32 v3, v4, v5
	global_store_dwordx2 v[30:31], v[2:3], off offset:1040
	v_pk_mul_f32 v[2:3], v[22:23], v[0:1] op_sel_hi:[1,0]
	v_pk_mul_f32 v[4:5], v[24:25], v[0:1] op_sel_hi:[1,0]
	s_nop 0
	v_pk_mul_f32 v[2:3], v[102:103], v[2:3]
	v_pk_mul_f32 v[4:5], v[104:105], v[4:5]
	v_cvt_pk_bf16_f32 v2, v2, v3
	v_cvt_pk_bf16_f32 v3, v4, v5
	global_store_dwordx2 v[30:31], v[2:3], off offset:1104
	s_nop 0
	v_pk_mul_f32 v[2:3], v[106:107], v[10:11]
	v_pk_mul_f32 v[10:11], v[66:67], v[0:1] op_sel_hi:[1,0]
	v_cvt_pk_bf16_f32 v2, v2, v3
	v_pk_mul_f32 v[4:5], v[108:109], v[10:11]
	v_pk_mul_f32 v[10:11], v[44:45], v[0:1] op_sel_hi:[1,0]
	v_cvt_pk_bf16_f32 v3, v4, v5
	global_store_dwordx2 v[30:31], v[2:3], off offset:1056
	v_pk_mul_f32 v[2:3], v[26:27], v[0:1] op_sel_hi:[1,0]
	v_pk_mul_f32 v[4:5], v[60:61], v[0:1] op_sel_hi:[1,0]
	s_nop 0
	v_pk_mul_f32 v[2:3], v[110:111], v[2:3]
	v_pk_mul_f32 v[4:5], v[112:113], v[4:5]
	v_cvt_pk_bf16_f32 v2, v2, v3
	v_cvt_pk_bf16_f32 v3, v4, v5
	global_store_dwordx2 v[30:31], v[2:3], off offset:1120
	s_nop 0
	v_pk_mul_f32 v[2:3], v[114:115], v[10:11]
	v_pk_mul_f32 v[10:11], v[16:17], v[0:1] op_sel_hi:[1,0]
	v_cvt_pk_bf16_f32 v2, v2, v3
	v_pk_mul_f32 v[4:5], v[116:117], v[10:11]
	s_nop 0
	v_cvt_pk_bf16_f32 v3, v4, v5
	global_store_dwordx2 v[30:31], v[2:3], off offset:1072
	v_pk_mul_f32 v[2:3], v[28:29], v[0:1] op_sel_hi:[1,0]
	v_pk_mul_f32 v[4:5], v[14:15], v[0:1] op_sel_hi:[1,0]
	s_nop 0
	v_pk_mul_f32 v[2:3], v[118:119], v[2:3]
	v_pk_mul_f32 v[30:31], v[120:121], v[4:5]
	v_cvt_pk_bf16_f32 v2, v2, v3

; #define PG8_STAGE(bufoff, gbase, voff) do { _Pragma("unroll") for (int _i = 0; _i < 2; ++_i) \
;         __builtin_amdgcn_global_load_lds((const unsigned*)((const char*)(gbase) + (voff)[_i]), (PG8_LAS unsigned*)(lds + (bufoff) + ldsw + _i * 8192), 16, 0, 0); } while (0)
; #define PG8_LDA(dst, b, h) do { _Pragma("unroll") for (int m = 0; m < 4; ++m) _Pragma("unroll") for (int k = 0; k < 2; ++k) dst[m][k] = *(const PG8_LAS bf16x8*)(lds + PG8_SA(b, h) + aoff + m * 2048 + k * 1024); } while (0)
; #define PG8_LDB(dst, b, h) do { _Pragma("unroll") for (int n = 0; n < 2; ++n) _Pragma("unroll") for (int k = 0; k < 2; ++k) dst[n][k] = *(const PG8_LAS bf16x8*)(lds + PG8_SB(b, h) + boff + n * 2048 + k * 1024); } while (0)
; #define PG8_MMA(ai, bj, At, Bt) do { __builtin_amdgcn_s_setprio(1); _Pragma("unroll") for (int m = 0; m < 4; ++m) _Pragma("unroll") for (int n = 0; n < 2; ++n) _Pragma("unroll") for (int k = 0; k < 2; ++k) \
;         acc[ai][bj][m][n] = __builtin_amdgcn_mfma_f32_16x16x32_bf16(Bt[n][k], At[m][k], acc[ai][bj][m][n], 0, 0, 0); __builtin_amdgcn_s_setprio(0); } while (0)
; #define PG8_WAIT_V(n) asm volatile("s_waitcnt vmcnt(" #n ")" ::: "memory")
; #define PG8_WAIT_L(n) asm volatile("s_waitcnt lgkmcnt(" #n ")" ::: "memory")
; template <class Epi, class Sched, bool ALIGN_EPI = false, bool SP2 = false>
; __device__ __forceinline__ void gemm_phase(PG8_LAS unsigned char* lds, const Gemm g, const Sched& S, const Epi& E) {
;     ...
;             const bool last = (t == nt - 2);
;             const char* a1 = cA + (size_t)(t + 1) * kstep;
;             const char* a2 = last ? nA : cA + (size_t)(t + 2) * kstep; const char* b2 = last ? nB : cB + (size_t)(t + 2) * kstep;
;             const char* a3 = a2 + kstep; const char* b3 = b2 + kstep;
;             if (last && has_next) S.a_ready(nxt);
;             if constexpr (SP2) {
;             PG8_LDB(B0, 0, 0); PG8_LDB(B1, 0, 1); PG8_SCHED; PG8_LDA(At, 0, 0); PG8_STAGE(PG8_SA(1, 1), a1 + hstep, voffA);
;             PG8_WAIT_V(8); PG8_WAIT_L(0); PG8_BAR; PG8_MMA(0, 0, At, B0); PG8_MMA(0, 1, At, B1); PG8_BAR; PG8_SCHED;
;             PG8_LDA(At, 0, 1); PG8_STAGE(PG8_SB(0, 0), b2, voffB); PG8_STAGE(PG8_SB(0, 1), b2 + hstep, voffB); PG8_STAGE(PG8_SA(0, 0), a2, voffA);
;             PG8_WAIT_V(8); PG8_WAIT_L(0); PG8_BAR; PG8_MMA(1, 0, At, B0); PG8_MMA(1, 1, At, B1); PG8_BAR; PG8_SCHED;
.LBB0_453:
	s_add_u32 s53, s18, 0xfffc0080
	s_addc_u32 s64, s19, -1
	s_add_i32 s70, 0, 0x10000
	s_cmp_eq_u32 s52, 12
	s_cselect_b32 s67, s30, s64
	s_cselect_b32 s66, s31, s53
	s_cselect_b32 s65, s34, s51
	s_cselect_b32 s64, s35, s49
	s_add_i32 s53, 0, 0x14000
	v_add_u32_e32 v142, s70, v223
	v_add_u32_e32 v158, s53, v223
	ds_read_b128 v[130:133], v142
	ds_read_b128 v[134:137], v142 offset:1024
	ds_read_b128 v[138:141], v142 offset:2048
	ds_read_b128 v[142:145], v142 offset:3072
	ds_read_b128 v[146:149], v158
	ds_read_b128 v[150:153], v158 offset:1024
	ds_read_b128 v[154:157], v158 offset:2048
	ds_read_b128 v[158:161], v158 offset:3072
	v_lshl_add_u64 v[208:209], s[18:19], 0, v[200:201]
	s_add_i32 m0, s25, 0xc000
	ds_read_b128 v[162:165], v225
	ds_read_b128 v[166:169], v225 offset:1024
	ds_read_b128 v[170:173], v225 offset:2048
	ds_read_b128 v[174:177], v225 offset:3072
	ds_read_b128 v[178:181], v225 offset:4096
	ds_read_b128 v[182:185], v225 offset:5120
	ds_read_b128 v[186:189], v225 offset:6144
	ds_read_b128 v[204:207], v225 offset:7168
	global_load_lds_dwordx4 v[208:209], off
	v_lshl_add_u64 v[208:209], s[18:19], 0, v[202:203]
	s_add_i32 m0, s25, 0xe000
	s_nop 0
	global_load_lds_dwordx4 v[208:209], off
	s_waitcnt vmcnt(8)
	s_waitcnt lgkmcnt(0)
	s_barrier
	s_setprio 1
	s_waitcnt lgkmcnt(0)
	v_mfma_f32_16x16x32_bf16 v[126:129], v[130:133], v[162:165], v[126:129]
	v_mfma_f32_16x16x32_bf16 v[122:125], v[138:141], v[162:165], v[122:125]
	v_mfma_f32_16x16x32_bf16 v[110:113], v[130:133], v[170:173], v[110:113]
	v_mfma_f32_16x16x32_bf16 v[106:109], v[138:141], v[170:173], v[106:109]
	v_mfma_f32_16x16x32_bf16 v[98:101], v[130:133], v[178:181], v[98:101]
	v_mfma_f32_16x16x32_bf16 v[90:93], v[138:141], v[178:181], v[90:93]
	v_mfma_f32_16x16x32_bf16 v[82:85], v[130:133], v[186:189], v[82:85]
	v_mfma_f32_16x16x32_bf16 v[74:77], v[138:141], v[186:189], v[74:77]
	v_mfma_f32_16x16x32_bf16 v[126:129], v[134:137], v[166:169], v[126:129]
	v_mfma_f32_16x16x32_bf16 v[122:125], v[142:145], v[166:169], v[122:125]
	v_mfma_f32_16x16x32_bf16 v[110:113], v[134:137], v[174:177], v[110:113]
	v_mfma_f32_16x16x32_bf16 v[106:109], v[142:145], v[174:177], v[106:109]
	v_mfma_f32_16x16x32_bf16 v[98:101], v[134:137], v[182:185], v[98:101]
	v_mfma_f32_16x16x32_bf16 v[90:93], v[142:145], v[182:185], v[90:93]
	v_mfma_f32_16x16x32_bf16 v[82:85], v[134:137], v[204:207], v[82:85]
	v_mfma_f32_16x16x32_bf16 v[74:77], v[142:145], v[204:207], v[74:77]
	s_setprio 0
	s_setprio 1
	v_mfma_f32_16x16x32_bf16 v[118:121], v[146:149], v[162:165], v[118:121]
	v_mfma_f32_16x16x32_bf16 v[114:117], v[154:157], v[162:165], v[114:117]
	v_mfma_f32_16x16x32_bf16 v[102:105], v[146:149], v[170:173], v[102:105]
	v_mfma_f32_16x16x32_bf16 v[94:97], v[154:157], v[170:173], v[94:97]
	v_mfma_f32_16x16x32_bf16 v[86:89], v[146:149], v[178:181], v[86:89]
	v_mfma_f32_16x16x32_bf16 v[78:81], v[154:157], v[178:181], v[78:81]
	v_mfma_f32_16x16x32_bf16 v[70:73], v[146:149], v[186:189], v[70:73]
	v_mfma_f32_16x16x32_bf16 v[66:69], v[154:157], v[186:189], v[66:69]
	v_mfma_f32_16x16x32_bf16 v[118:121], v[150:153], v[166:169], v[118:121]
	v_mfma_f32_16x16x32_bf16 v[114:117], v[158:161], v[166:169], v[114:117]
	v_mfma_f32_16x16x32_bf16 v[102:105], v[150:153], v[174:177], v[102:105]
	v_mfma_f32_16x16x32_bf16 v[94:97], v[158:161], v[174:177], v[94:97]
	v_mfma_f32_16x16x32_bf16 v[86:89], v[150:153], v[182:185], v[86:89]
	v_mfma_f32_16x16x32_bf16 v[78:81], v[158:161], v[182:185], v[78:81]
	v_mfma_f32_16x16x32_bf16 v[70:73], v[150:153], v[204:207], v[70:73]
	v_mfma_f32_16x16x32_bf16 v[66:69], v[158:161], v[204:207], v[66:69]
	s_setprio 0
	s_barrier
	s_add_i32 s70, s70, s24
	v_lshl_add_u64 v[208:209], s[64:65], 0, v[0:1]
	s_mov_b32 m0, s70
	ds_read_b128 v[162:165], v225 offset:16384
	ds_read_b128 v[166:169], v225 offset:17408
	ds_read_b128 v[170:173], v225 offset:18432
	ds_read_b128 v[174:177], v225 offset:19456
	ds_read_b128 v[178:181], v225 offset:20480
	ds_read_b128 v[182:185], v225 offset:21504
	ds_read_b128 v[186:189], v225 offset:22528
	ds_read_b128 v[204:207], v225 offset:23552
	global_load_lds_dwordx4 v[208:209], off
	s_add_i32 m0, s70, 0x2000
	s_add_u32 s70, s64, 0x40000
	v_lshl_add_u64 v[210:211], s[64:65], 0, v[198:199]
	s_addc_u32 s71, s65, 0
	s_add_i32 s53, s53, s24
	global_load_lds_dwordx4 v[210:211], off
	v_lshl_add_u64 v[212:213], s[70:71], 0, v[0:1]
	s_mov_b32 m0, s53
	v_lshl_add_u64 v[214:215], s[66:67], 0, v[196:197]
	global_load_lds_dwordx4 v[212:213], off
	v_lshl_add_u64 v[212:213], s[70:71], 0, v[198:199]
	s_add_i32 m0, s53, 0x2000
	s_nop 0
	global_load_lds_dwordx4 v[212:213], off
	v_lshl_add_u64 v[212:213], s[66:67], 0, v[194:195]
	s_mov_b32 m0, s25
	s_nop 0
	global_load_lds_dwordx4 v[212:213], off
	s_mov_b32 m0, s26
	s_nop 0
	global_load_lds_dwordx4 v[214:215], off
	s_waitcnt vmcnt(8)
	s_waitcnt lgkmcnt(0)
	s_barrier
; #define PG8_STAGE(bufoff, gbase, voff) do { _Pragma("unroll") for (int _i = 0; _i < 2; ++_i) \
;         __builtin_amdgcn_global_load_lds((const unsigned*)((const char*)(gbase) + (voff)[_i]), (PG8_LAS unsigned*)(lds + (bufoff) + ldsw + _i * 8192), 16, 0, 0); } while (0)
; #define PG8_LDA(dst, b, h) do { _Pragma("unroll") for (int m = 0; m < 4; ++m) _Pragma("unroll") for (int k = 0; k < 2; ++k) dst[m][k] = *(const PG8_LAS bf16x8*)(lds + PG8_SA(b, h) + aoff + m * 2048 + k * 1024); } while (0)
; #define PG8_LDB(dst, b, h) do { _Pragma("unroll") for (int n = 0; n < 2; ++n) _Pragma("unroll") for (int k = 0; k < 2; ++k) dst[n][k] = *(const PG8_LAS bf16x8*)(lds + PG8_SB(b, h) + boff + n * 2048 + k * 1024); } while (0)
; #define PG8_MMA(ai, bj, At, Bt) do { __builtin_amdgcn_s_setprio(1); _Pragma("unroll") for (int m = 0; m < 4; ++m) _Pragma("unroll") for (int n = 0; n < 2; ++n) _Pragma("unroll") for (int k = 0; k < 2; ++k) \
;         acc[ai][bj][m][n] = __builtin_amdgcn_mfma_f32_16x16x32_bf16(Bt[n][k], At[m][k], acc[ai][bj][m][n], 0, 0, 0); __builtin_amdgcn_s_setprio(0); } while (0)
; #define PG8_WAIT_V(n) asm volatile("s_waitcnt vmcnt(" #n ")" ::: "memory")
; #define PG8_WAIT_L(n) asm volatile("s_waitcnt lgkmcnt(" #n ")" ::: "memory")
; #define PG8_BAR __builtin_amdgcn_s_barrier()
; #define PG8_SCHED __builtin_amdgcn_sched_barrier(0)
; template <class Epi, class Sched, bool ALIGN_EPI = false, bool SP2 = false>
; __device__ __forceinline__ void gemm_phase(PG8_LAS unsigned char* lds, const Gemm g, const Sched& S, const Epi& E) {
;     ...
;             PG8_WAIT_V(8); PG8_WAIT_L(0); PG8_BAR; PG8_MMA(1, 0, At, B0); PG8_MMA(1, 1, At, B1); PG8_BAR; PG8_SCHED;
;             PG8_LDB(B0, 1, 0); PG8_LDB(B1, 1, 1); PG8_SCHED; PG8_LDA(At, 1, 0); PG8_STAGE(PG8_SA(0, 1), a2 + hstep, voffA);
;             PG8_WAIT_V(8); PG8_WAIT_L(0); PG8_BAR; PG8_MMA(0, 0, At, B0); PG8_MMA(0, 1, At, B1); PG8_BAR; PG8_SCHED;
	s_setprio 1
	s_waitcnt lgkmcnt(0)
	v_mfma_f32_16x16x32_bf16 v[62:65], v[130:133], v[162:165], v[62:65]
	v_mfma_f32_16x16x32_bf16 v[58:61], v[138:141], v[162:165], v[58:61]
	v_mfma_f32_16x16x32_bf16 v[50:53], v[130:133], v[170:173], v[50:53]
	v_mfma_f32_16x16x32_bf16 v[42:45], v[138:141], v[170:173], v[42:45]
	v_mfma_f32_16x16x32_bf16 v[34:37], v[130:133], v[178:181], v[34:37]
	v_mfma_f32_16x16x32_bf16 v[26:29], v[138:141], v[178:181], v[26:29]
	v_mfma_f32_16x16x32_bf16 v[18:21], v[130:133], v[186:189], v[18:21]
	v_mfma_f32_16x16x32_bf16 v[10:13], v[138:141], v[186:189], v[10:13]
	v_mfma_f32_16x16x32_bf16 v[62:65], v[134:137], v[166:169], v[62:65]
	v_mfma_f32_16x16x32_bf16 v[58:61], v[142:145], v[166:169], v[58:61]
	v_mfma_f32_16x16x32_bf16 v[50:53], v[134:137], v[174:177], v[50:53]
	v_mfma_f32_16x16x32_bf16 v[42:45], v[142:145], v[174:177], v[42:45]
	v_mfma_f32_16x16x32_bf16 v[34:37], v[134:137], v[182:185], v[34:37]
	v_mfma_f32_16x16x32_bf16 v[26:29], v[142:145], v[182:185], v[26:29]
	v_mfma_f32_16x16x32_bf16 v[18:21], v[134:137], v[204:207], v[18:21]
	v_mfma_f32_16x16x32_bf16 v[10:13], v[142:145], v[204:207], v[10:13]
	s_setprio 0
	s_setprio 1
	v_mfma_f32_16x16x32_bf16 v[54:57], v[146:149], v[162:165], v[54:57]
	v_mfma_f32_16x16x32_bf16 v[46:49], v[154:157], v[162:165], v[46:49]
	v_mfma_f32_16x16x32_bf16 v[38:41], v[146:149], v[170:173], v[38:41]
	v_mfma_f32_16x16x32_bf16 v[30:33], v[154:157], v[170:173], v[30:33]
	v_mfma_f32_16x16x32_bf16 v[22:25], v[146:149], v[178:181], v[22:25]
	v_mfma_f32_16x16x32_bf16 v[14:17], v[154:157], v[178:181], v[14:17]
	v_mfma_f32_16x16x32_bf16 v[6:9], v[146:149], v[186:189], v[6:9]
	v_mfma_f32_16x16x32_bf16 v[2:5], v[154:157], v[186:189], v[2:5]
	v_mfma_f32_16x16x32_bf16 v[54:57], v[150:153], v[166:169], v[54:57]
	v_mfma_f32_16x16x32_bf16 v[46:49], v[158:161], v[166:169], v[46:49]
	v_mfma_f32_16x16x32_bf16 v[38:41], v[150:153], v[174:177], v[38:41]
	v_mfma_f32_16x16x32_bf16 v[30:33], v[158:161], v[174:177], v[30:33]
	v_mfma_f32_16x16x32_bf16 v[22:25], v[150:153], v[182:185], v[22:25]
	v_mfma_f32_16x16x32_bf16 v[14:17], v[158:161], v[182:185], v[14:17]
	v_mfma_f32_16x16x32_bf16 v[6:9], v[150:153], v[204:207], v[6:9]
	v_mfma_f32_16x16x32_bf16 v[2:5], v[158:161], v[204:207], v[2:5]
	s_setprio 0
	s_barrier
	s_add_i32 s53, 0, 0x18000
	s_add_i32 s70, 0, 0x1c000
	v_add_u32_e32 v142, s53, v223
	v_add_u32_e32 v158, s70, v223
	ds_read_b128 v[130:133], v142
	ds_read_b128 v[134:137], v142 offset:1024
	ds_read_b128 v[138:141], v142 offset:2048
	ds_read_b128 v[142:145], v142 offset:3072
	ds_read_b128 v[146:149], v158
	ds_read_b128 v[150:153], v158 offset:1024
	ds_read_b128 v[154:157], v158 offset:2048
	ds_read_b128 v[158:161], v158 offset:3072
	s_add_u32 s66, s66, 0x40000
	s_addc_u32 s67, s67, 0
	s_mov_b32 m0, s27
	v_lshl_add_u64 v[216:217], s[66:67], 0, v[194:195]
	ds_read_b128 v[162:165], v225 offset:32768
	ds_read_b128 v[166:169], v225 offset:33792
	ds_read_b128 v[170:173], v225 offset:34816
	ds_read_b128 v[174:177], v225 offset:35840
	ds_read_b128 v[178:181], v225 offset:36864
	ds_read_b128 v[182:185], v225 offset:37888
	ds_read_b128 v[186:189], v225 offset:38912
	ds_read_b128 v[204:207], v225 offset:39936
	global_load_lds_dwordx4 v[216:217], off
	v_lshl_add_u64 v[216:217], s[66:67], 0, v[196:197]
	s_mov_b32 m0, s28
	s_nop 0
	global_load_lds_dwordx4 v[216:217], off
	s_waitcnt vmcnt(8)
	s_waitcnt lgkmcnt(0)
	s_barrier
	s_setprio 1
	s_waitcnt lgkmcnt(0)
	v_mfma_f32_16x16x32_bf16 v[126:129], v[130:133], v[162:165], v[126:129]
	v_mfma_f32_16x16x32_bf16 v[122:125], v[138:141], v[162:165], v[122:125]
	v_mfma_f32_16x16x32_bf16 v[110:113], v[130:133], v[170:173], v[110:113]
	v_mfma_f32_16x16x32_bf16 v[106:109], v[138:141], v[170:173], v[106:109]
	v_mfma_f32_16x16x32_bf16 v[98:101], v[130:133], v[178:181], v[98:101]
	v_mfma_f32_16x16x32_bf16 v[90:93], v[138:141], v[178:181], v[90:93]
	v_mfma_f32_16x16x32_bf16 v[82:85], v[130:133], v[186:189], v[82:85]
	v_mfma_f32_16x16x32_bf16 v[74:77], v[138:141], v[186:189], v[74:77]
	v_mfma_f32_16x16x32_bf16 v[126:129], v[134:137], v[166:169], v[126:129]
	v_mfma_f32_16x16x32_bf16 v[122:125], v[142:145], v[166:169], v[122:125]
	v_mfma_f32_16x16x32_bf16 v[110:113], v[134:137], v[174:177], v[110:113]
	v_mfma_f32_16x16x32_bf16 v[106:109], v[142:145], v[174:177], v[106:109]
	v_mfma_f32_16x16x32_bf16 v[98:101], v[134:137], v[182:185], v[98:101]
	v_mfma_f32_16x16x32_bf16 v[90:93], v[142:145], v[182:185], v[90:93]
	v_mfma_f32_16x16x32_bf16 v[82:85], v[134:137], v[204:207], v[82:85]
	v_mfma_f32_16x16x32_bf16 v[74:77], v[142:145], v[204:207], v[74:77]
	s_setprio 0
	s_setprio 1
	v_mfma_f32_16x16x32_bf16 v[118:121], v[146:149], v[162:165], v[118:121]
	v_mfma_f32_16x16x32_bf16 v[114:117], v[154:157], v[162:165], v[114:117]
	v_mfma_f32_16x16x32_bf16 v[102:105], v[146:149], v[170:173], v[102:105]
	v_mfma_f32_16x16x32_bf16 v[94:97], v[154:157], v[170:173], v[94:97]
	v_mfma_f32_16x16x32_bf16 v[86:89], v[146:149], v[178:181], v[86:89]
	v_mfma_f32_16x16x32_bf16 v[78:81], v[154:157], v[178:181], v[78:81]
	v_mfma_f32_16x16x32_bf16 v[70:73], v[146:149], v[186:189], v[70:73]
	v_mfma_f32_16x16x32_bf16 v[66:69], v[154:157], v[186:189], v[66:69]
	v_mfma_f32_16x16x32_bf16 v[118:121], v[150:153], v[166:169], v[118:121]
	v_mfma_f32_16x16x32_bf16 v[114:117], v[158:161], v[166:169], v[114:117]
	v_mfma_f32_16x16x32_bf16 v[102:105], v[150:153], v[174:177], v[102:105]
	v_mfma_f32_16x16x32_bf16 v[94:97], v[158:161], v[174:177], v[94:97]
	v_mfma_f32_16x16x32_bf16 v[86:89], v[150:153], v[182:185], v[86:89]
	v_mfma_f32_16x16x32_bf16 v[78:81], v[158:161], v[182:185], v[78:81]
	v_mfma_f32_16x16x32_bf16 v[70:73], v[150:153], v[204:207], v[70:73]
	v_mfma_f32_16x16x32_bf16 v[66:69], v[158:161], v[204:207], v[66:69]
	s_setprio 0
	s_barrier
; #define PG8_STAGE(bufoff, gbase, voff) do { _Pragma("unroll") for (int _i = 0; _i < 2; ++_i) \
;         __builtin_amdgcn_global_load_lds((const unsigned*)((const char*)(gbase) + (voff)[_i]), (PG8_LAS unsigned*)(lds + (bufoff) + ldsw + _i * 8192), 16, 0, 0); } while (0)
; #define PG8_LDA(dst, b, h) do { _Pragma("unroll") for (int m = 0; m < 4; ++m) _Pragma("unroll") for (int k = 0; k < 2; ++k) dst[m][k] = *(const PG8_LAS bf16x8*)(lds + PG8_SA(b, h) + aoff + m * 2048 + k * 1024); } while (0)
; #define PG8_MMA(ai, bj, At, Bt) do { __builtin_amdgcn_s_setprio(1); _Pragma("unroll") for (int m = 0; m < 4; ++m) _Pragma("unroll") for (int n = 0; n < 2; ++n) _Pragma("unroll") for (int k = 0; k < 2; ++k) \
;         acc[ai][bj][m][n] = __builtin_amdgcn_mfma_f32_16x16x32_bf16(Bt[n][k], At[m][k], acc[ai][bj][m][n], 0, 0, 0); __builtin_amdgcn_s_setprio(0); } while (0)
; #define PG8_WAIT_V(n) asm volatile("s_waitcnt vmcnt(" #n ")" ::: "memory")
; #define PG8_WAIT_L(n) asm volatile("s_waitcnt lgkmcnt(" #n ")" ::: "memory")
; #define PG8_BAR __builtin_amdgcn_s_barrier()
; #define PG8_SCHED __builtin_amdgcn_sched_barrier(0)
; template <class Epi, class Sched, bool ALIGN_EPI = false, bool SP2 = false>
; __device__ __forceinline__ void gemm_phase(PG8_LAS unsigned char* lds, const Gemm g, const Sched& S, const Epi& E) {
;     ...
;             PG8_LDA(At, 1, 1); PG8_STAGE(PG8_SB(1, 0), b3, voffB); PG8_STAGE(PG8_SB(1, 1), b3 + hstep, voffB); PG8_STAGE(PG8_SA(1, 0), a3, voffA);
;             PG8_WAIT_V(8); PG8_WAIT_L(0); PG8_BAR; PG8_MMA(1, 0, At, B0); PG8_MMA(1, 1, At, B1); PG8_BAR; PG8_SCHED;
;     ...
;         if constexpr (ALIGN_EPI) { if (wr == 0) PG8_BAR; }
	s_add_i32 s53, s53, s24
	v_lshl_add_u64 v[208:209], v[208:209], 0, s[8:9]
	s_mov_b32 m0, s53
	ds_read_b128 v[162:165], v225 offset:49152
	ds_read_b128 v[166:169], v225 offset:50176
	ds_read_b128 v[170:173], v225 offset:51200
	ds_read_b128 v[174:177], v225 offset:52224
	ds_read_b128 v[178:181], v225 offset:53248
	ds_read_b128 v[182:185], v225 offset:54272
	ds_read_b128 v[186:189], v225 offset:55296
	ds_read_b128 v[204:207], v225 offset:56320
	global_load_lds_dwordx4 v[208:209], off
	s_add_i32 m0, s53, 0x2000
	s_add_u32 s64, s64, 0x40080
	v_lshl_add_u64 v[208:209], v[210:211], 0, s[8:9]
	s_addc_u32 s65, s65, 0
	s_add_i32 s53, s70, s24
	global_load_lds_dwordx4 v[208:209], off
	v_lshl_add_u64 v[208:209], s[64:65], 0, v[0:1]
	s_mov_b32 m0, s53
	s_nop 0
	global_load_lds_dwordx4 v[208:209], off
	v_lshl_add_u64 v[208:209], s[64:65], 0, v[198:199]
	s_add_i32 m0, s53, 0x2000
	s_nop 0
	global_load_lds_dwordx4 v[208:209], off
	v_lshl_add_u64 v[208:209], v[212:213], 0, s[8:9]
	s_mov_b32 m0, s29
	s_nop 0
	global_load_lds_dwordx4 v[208:209], off
	v_lshl_add_u64 v[208:209], v[214:215], 0, s[8:9]
	s_mov_b32 m0, s61
	s_nop 0
	global_load_lds_dwordx4 v[208:209], off
	s_waitcnt vmcnt(8)
	s_waitcnt lgkmcnt(0)
	s_barrier
	s_setprio 1
	s_waitcnt lgkmcnt(0)
	v_mfma_f32_16x16x32_bf16 v[62:65], v[130:133], v[162:165], v[62:65]
	v_mfma_f32_16x16x32_bf16 v[58:61], v[138:141], v[162:165], v[58:61]
	v_mfma_f32_16x16x32_bf16 v[50:53], v[130:133], v[170:173], v[50:53]
	v_mfma_f32_16x16x32_bf16 v[42:45], v[138:141], v[170:173], v[42:45]
	v_mfma_f32_16x16x32_bf16 v[34:37], v[130:133], v[178:181], v[34:37]
	v_mfma_f32_16x16x32_bf16 v[26:29], v[138:141], v[178:181], v[26:29]
	v_mfma_f32_16x16x32_bf16 v[18:21], v[130:133], v[186:189], v[18:21]
	v_mfma_f32_16x16x32_bf16 v[10:13], v[138:141], v[186:189], v[10:13]
	v_mfma_f32_16x16x32_bf16 v[62:65], v[134:137], v[166:169], v[62:65]
	v_mfma_f32_16x16x32_bf16 v[58:61], v[142:145], v[166:169], v[58:61]
	v_mfma_f32_16x16x32_bf16 v[50:53], v[134:137], v[174:177], v[50:53]
	v_mfma_f32_16x16x32_bf16 v[42:45], v[142:145], v[174:177], v[42:45]
	v_mfma_f32_16x16x32_bf16 v[34:37], v[134:137], v[182:185], v[34:37]
	v_mfma_f32_16x16x32_bf16 v[26:29], v[142:145], v[182:185], v[26:29]
	v_mfma_f32_16x16x32_bf16 v[18:21], v[134:137], v[204:207], v[18:21]
	v_mfma_f32_16x16x32_bf16 v[10:13], v[142:145], v[204:207], v[10:13]
	s_setprio 0
	s_setprio 1
	v_mfma_f32_16x16x32_bf16 v[54:57], v[146:149], v[162:165], v[54:57]
	v_mfma_f32_16x16x32_bf16 v[46:49], v[154:157], v[162:165], v[46:49]
	v_mfma_f32_16x16x32_bf16 v[38:41], v[146:149], v[170:173], v[38:41]
	v_mfma_f32_16x16x32_bf16 v[30:33], v[154:157], v[170:173], v[30:33]
	v_mfma_f32_16x16x32_bf16 v[22:25], v[146:149], v[178:181], v[22:25]
	v_mfma_f32_16x16x32_bf16 v[14:17], v[154:157], v[178:181], v[14:17]
	v_mfma_f32_16x16x32_bf16 v[6:9], v[146:149], v[186:189], v[6:9]
	v_mfma_f32_16x16x32_bf16 v[2:5], v[154:157], v[186:189], v[2:5]
	v_mfma_f32_16x16x32_bf16 v[54:57], v[150:153], v[166:169], v[54:57]
	v_mfma_f32_16x16x32_bf16 v[46:49], v[158:161], v[166:169], v[46:49]
	v_mfma_f32_16x16x32_bf16 v[38:41], v[150:153], v[174:177], v[38:41]
	v_mfma_f32_16x16x32_bf16 v[30:33], v[158:161], v[174:177], v[30:33]
	v_mfma_f32_16x16x32_bf16 v[22:25], v[150:153], v[182:185], v[22:25]
	v_mfma_f32_16x16x32_bf16 v[14:17], v[158:161], v[182:185], v[14:17]
	v_mfma_f32_16x16x32_bf16 v[6:9], v[150:153], v[204:207], v[6:9]
	v_mfma_f32_16x16x32_bf16 v[2:5], v[158:161], v[204:207], v[2:5]
	s_setprio 0
	s_barrier
	s_add_i32 s52, s52, 2
	s_add_u32 s18, s18, 0x100
	s_addc_u32 s19, s19, 0
	s_add_u32 s49, s49, 0x100
	s_addc_u32 s51, s51, 0
	s_cmp_gt_u32 s52, 13
	s_cbranch_scc0 .LBB0_453


;     __device__ __forceinline__ void operator()(const f32x4 (&acc)[2][2][4][2], const pg8::Unit& u, int wr, int wc, int fr, int fq) const {
;     ...
;             u32x4 w[2][4][2];
; #pragma unroll
;             for (int ai = 0; ai < 2; ++ai)
; #pragma unroll
;                 for (int m = 0; m < 4; ++m)
; #pragma unroll
;                     for (int bj = 0; bj < 2; ++bj) w[ai][m][bj] = *(const u32x4*)(xb + (size_t)(row0 + ai * 128 + m * 16) * DM + col0 + bj * 128);
; #pragma unroll
;             for (int ai = 0; ai < 2; ++ai)
; #pragma unroll
;                 for (int m = 0; m < 4; ++m) { float q = 0.f;
; #pragma unroll
;                     for (int bj = 0; bj < 2; ++bj) { const u32x4 t = w[ai][m][bj];
;                         const f32x4 b0 = {__uint_as_float(t.x << 16), __uint_as_float(t.x & 0xffff0000u), __uint_as_float(t.y << 16), __uint_as_float(t.y & 0xffff0000u)};
;                         const f32x4 b1 = {__uint_as_float(t.z << 16), __uint_as_float(t.z & 0xffff0000u), __uint_as_float(t.w << 16), __uint_as_float(t.w & 0xffff0000u)};
;                         q += emit(b0 + acc[ai][bj][m][0] * alpha, b1 + acc[ai][bj][m][1] * alpha, (size_t)(row0 + ai * 128 + m * 16) * DM + col0 + bj * 128); }
;                     sq[ai][m] = q; }
;         }
;         if (MODE != 2) {
; #pragma unroll
;             for (int ai = 0; ai < 2; ++ai)
; #pragma unroll
;                 for (int m = 0; m < 4; ++m) sq[ai][m] += __shfl_xor(sq[ai][m], 16);
; #pragma unroll
;             for (int ai = 0; ai < 2; ++ai)
; #pragma unroll
;                 for (int m = 0; m < 4; ++m) sq[ai][m] += __shfl_xor(sq[ai][m], 32);
;             if (fq == 0) {
; #pragma unroll
;                 for (int ai = 0; ai < 2; ++ai)
; #pragma unroll
;                     for (int m = 0; m < 4; ++m) atomicAdd(ssn + row0 + ai * 128 + m * 16, (u64)(sq[ai][m] * SS_SCALE + 0.5f)); }
;         }
;     }
;     __device__ __forceinline__ float emit(const f32x4 v0, const f32x4 v1, size_t off) const {
;         if (MODE == 2) { *(f32x4*)(out + off) = v0; *(f32x4*)(out + off + 4) = v1; return 0.f; }
.LBB0_456:
	v_lshl_add_u32 v220, s62, 8, v222
	v_lshl_or_b32 v218, s60, 8, v224
	v_ashrrev_i32_e32 v219, 31, v218
	v_ashrrev_i32_e32 v221, 31, v220
	v_lshl_add_u64 v[130:131], v[218:219], 1, s[96:97]
	v_lshlrev_b64 v[132:133], 11, v[220:221]
	v_lshl_add_u64 v[132:133], v[130:131], 0, v[132:133]
	global_load_dwordx4 v[238:241], v[132:133], off
	global_load_dwordx4 v[186:189], v[132:133], off offset:256
	v_or_b32_e32 v216, 16, v220
	v_ashrrev_i32_e32 v217, 31, v216
	v_lshlrev_b64 v[132:133], 11, v[216:217]
	v_lshl_add_u64 v[132:133], v[130:131], 0, v[132:133]
	global_load_dwordx4 v[182:185], v[132:133], off
	global_load_dwordx4 v[178:181], v[132:133], off offset:256
	v_or_b32_e32 v214, 32, v220
	v_ashrrev_i32_e32 v215, 31, v214
	v_lshlrev_b64 v[132:133], 11, v[214:215]
	v_lshl_add_u64 v[132:133], v[130:131], 0, v[132:133]
	global_load_dwordx4 v[174:177], v[132:133], off
	global_load_dwordx4 v[170:173], v[132:133], off offset:256
	v_or_b32_e32 v212, 48, v220
	v_ashrrev_i32_e32 v213, 31, v212
	v_lshlrev_b64 v[132:133], 11, v[212:213]
	v_lshl_add_u64 v[132:133], v[130:131], 0, v[132:133]
	global_load_dwordx4 v[166:169], v[132:133], off
	global_load_dwordx4 v[162:165], v[132:133], off offset:256
	v_add_u32_e32 v210, 0x80, v220
	v_ashrrev_i32_e32 v211, 31, v210
	v_lshlrev_b64 v[132:133], 11, v[210:211]
	v_lshl_add_u64 v[132:133], v[130:131], 0, v[132:133]
	global_load_dwordx4 v[158:161], v[132:133], off
	global_load_dwordx4 v[154:157], v[132:133], off offset:256
	v_add_u32_e32 v208, 0x90, v220
	v_ashrrev_i32_e32 v209, 31, v208
	v_lshlrev_b64 v[132:133], 11, v[208:209]
	v_lshl_add_u64 v[132:133], v[130:131], 0, v[132:133]
	global_load_dwordx4 v[150:153], v[132:133], off
	global_load_dwordx4 v[146:149], v[132:133], off offset:256
	v_add_u32_e32 v206, 0xa0, v220
	v_ashrrev_i32_e32 v207, 31, v206
	v_lshlrev_b64 v[132:133], 11, v[206:207]
	v_lshl_add_u64 v[132:133], v[130:131], 0, v[132:133]
	global_load_dwordx4 v[142:145], v[132:133], off
	global_load_dwordx4 v[134:137], v[132:133], off offset:256
	v_add_u32_e32 v204, 0xb0, v220
	v_ashrrev_i32_e32 v205, 31, v204
	v_lshlrev_b64 v[132:133], 11, v[204:205]
	v_lshl_add_u64 v[130:131], v[130:131], 0, v[132:133]
	global_load_dwordx4 v[138:141], v[130:131], off
	s_nop 0
	global_load_dwordx4 v[130:133], v[130:131], off offset:256
	s_and_b64 vcc, exec, s[46:47]
	s_cbranch_vccz .Lalign_go_2
	s_barrier
.Lalign_go_2:
	s_mov_b64 s[18:19], -1
	s_andn2_b64 vcc, exec, s[54:55]
	s_waitcnt vmcnt(0)
	v_lshlrev_b32_e32 v226, 16, v238
	v_and_b32_e32 v227, 0xffff0000, v238
	v_lshlrev_b32_e32 v238, 16, v239
	v_and_b32_e32 v239, 0xffff0000, v239
	v_lshlrev_b32_e32 v242, 16, v240
	v_and_b32_e32 v243, 0xffff0000, v240
	v_lshlrev_b32_e32 v240, 16, v241
	v_and_b32_e32 v241, 0xffff0000, v241
	v_pk_fma_f32 v[128:129], v[128:129], 0.5, v[238:239] op_sel_hi:[1,0,1]
	v_pk_fma_f32 v[238:239], v[122:123], 0.5, v[242:243] op_sel_hi:[1,0,1]
	v_lshlrev_b64 v[122:123], 12, v[220:221]
	v_pk_fma_f32 v[240:241], v[124:125], 0.5, v[240:241] op_sel_hi:[1,0,1]
	v_lshl_add_u64 v[124:125], s[88:89], 0, v[122:123]
	v_lshlrev_b64 v[122:123], 2, v[218:219]
	v_pk_fma_f32 v[126:127], v[126:127], 0.5, v[226:227] op_sel_hi:[1,0,1]
	v_lshl_add_u64 v[124:125], v[124:125], 0, v[122:123]
	global_store_dwordx4 v[124:125], v[126:129], off
	global_store_dwordx4 v[124:125], v[238:241], off offset:16
	s_nop 0
	v_lshlrev_b32_e32 v126, 16, v186
	v_and_b32_e32 v127, 0xffff0000, v186
	v_lshlrev_b32_e32 v128, 16, v187
	v_and_b32_e32 v129, 0xffff0000, v187
	v_lshlrev_b32_e32 v186, 16, v188
	v_and_b32_e32 v187, 0xffff0000, v188
	v_lshlrev_b32_e32 v188, 16, v189
	v_and_b32_e32 v189, 0xffff0000, v189
	v_pk_fma_f32 v[120:121], v[120:121], 0.5, v[128:129] op_sel_hi:[1,0,1]
	v_pk_fma_f32 v[118:119], v[118:119], 0.5, v[126:127] op_sel_hi:[1,0,1]
	v_pk_fma_f32 v[114:115], v[114:115], 0.5, v[186:187] op_sel_hi:[1,0,1]
	v_pk_fma_f32 v[116:117], v[116:117], 0.5, v[188:189] op_sel_hi:[1,0,1]
	global_store_dwordx4 v[124:125], v[118:121], off offset:512
	global_store_dwordx4 v[124:125], v[114:117], off offset:528
	s_nop 0
	v_lshlrev_b32_e32 v118, 16, v184
	v_lshlrev_b32_e32 v114, 16, v182
	v_and_b32_e32 v115, 0xffff0000, v182
	v_pk_fma_f32 v[110:111], v[110:111], 0.5, v[114:115] op_sel_hi:[1,0,1]
	v_lshlrev_b64 v[114:115], 12, v[216:217]
	v_lshlrev_b32_e32 v116, 16, v183
	v_and_b32_e32 v117, 0xffff0000, v183
	v_and_b32_e32 v119, 0xffff0000, v184
	v_lshlrev_b32_e32 v120, 16, v185
	v_and_b32_e32 v121, 0xffff0000, v185
	v_lshl_add_u64 v[114:115], s[88:89], 0, v[114:115]
	v_pk_fma_f32 v[112:113], v[112:113], 0.5, v[116:117] op_sel_hi:[1,0,1]
	v_pk_fma_f32 v[108:109], v[108:109], 0.5, v[120:121] op_sel_hi:[1,0,1]
	v_pk_fma_f32 v[106:107], v[106:107], 0.5, v[118:119] op_sel_hi:[1,0,1]
	v_lshl_add_u64 v[114:115], v[114:115], 0, v[122:123]
	global_store_dwordx4 v[114:115], v[110:113], off
	global_store_dwordx4 v[114:115], v[106:109], off offset:16
	s_nop 0
	v_lshlrev_b32_e32 v110, 16, v180
	v_lshlrev_b32_e32 v106, 16, v178
	v_and_b32_e32 v107, 0xffff0000, v178
	v_lshlrev_b32_e32 v108, 16, v179
	v_and_b32_e32 v109, 0xffff0000, v179
	v_and_b32_e32 v111, 0xffff0000, v180
	v_lshlrev_b32_e32 v112, 16, v181
	v_and_b32_e32 v113, 0xffff0000, v181
	v_pk_fma_f32 v[104:105], v[104:105], 0.5, v[108:109] op_sel_hi:[1,0,1]
	v_pk_fma_f32 v[102:103], v[102:103], 0.5, v[106:107] op_sel_hi:[1,0,1]
	v_pk_fma_f32 v[94:95], v[94:95], 0.5, v[110:111] op_sel_hi:[1,0,1]
	v_pk_fma_f32 v[96:97], v[96:97], 0.5, v[112:113] op_sel_hi:[1,0,1]
	global_store_dwordx4 v[114:115], v[102:105], off offset:512
	global_store_dwordx4 v[114:115], v[94:97], off offset:528
	s_nop 0
	v_lshlrev_b32_e32 v102, 16, v176
;     __device__ __forceinline__ void operator()(const f32x4 (&acc)[2][2][4][2], const pg8::Unit& u, int wr, int wc, int fr, int fq) const {
;     ...
;             for (int ai = 0; ai < 2; ++ai)
; #pragma unroll
;                 for (int m = 0; m < 4; ++m) { float q = 0.f;
; #pragma unroll
;                     for (int bj = 0; bj < 2; ++bj) { const u32x4 t = w[ai][m][bj];
;                         const f32x4 b0 = {__uint_as_float(t.x << 16), __uint_as_float(t.x & 0xffff0000u), __uint_as_float(t.y << 16), __uint_as_float(t.y & 0xffff0000u)};
;                         const f32x4 b1 = {__uint_as_float(t.z << 16), __uint_as_float(t.z & 0xffff0000u), __uint_as_float(t.w << 16), __uint_as_float(t.w & 0xffff0000u)};
;                         q += emit(b0 + acc[ai][bj][m][0] * alpha, b1 + acc[ai][bj][m][1] * alpha, (size_t)(row0 + ai * 128 + m * 16) * DM + col0 + bj * 128); }
;     __device__ __forceinline__ float emit(const f32x4 v0, const f32x4 v1, size_t off) const {
;         if (MODE == 2) { *(f32x4*)(out + off) = v0; *(f32x4*)(out + off + 4) = v1; return 0.f; }
	v_lshlrev_b32_e32 v94, 16, v174
	v_and_b32_e32 v95, 0xffff0000, v174
	v_pk_fma_f32 v[94:95], v[98:99], 0.5, v[94:95] op_sel_hi:[1,0,1]
	v_lshlrev_b64 v[98:99], 12, v[214:215]
	v_lshlrev_b32_e32 v96, 16, v175
	v_and_b32_e32 v97, 0xffff0000, v175
	v_and_b32_e32 v103, 0xffff0000, v176
	v_lshlrev_b32_e32 v104, 16, v177
	v_and_b32_e32 v105, 0xffff0000, v177
	v_lshl_add_u64 v[98:99], s[88:89], 0, v[98:99]
	v_pk_fma_f32 v[96:97], v[100:101], 0.5, v[96:97] op_sel_hi:[1,0,1]
	v_pk_fma_f32 v[92:93], v[92:93], 0.5, v[104:105] op_sel_hi:[1,0,1]
	v_pk_fma_f32 v[90:91], v[90:91], 0.5, v[102:103] op_sel_hi:[1,0,1]
	v_lshl_add_u64 v[98:99], v[98:99], 0, v[122:123]
	global_store_dwordx4 v[98:99], v[94:97], off
	global_store_dwordx4 v[98:99], v[90:93], off offset:16
	s_nop 0
	v_lshlrev_b32_e32 v94, 16, v172
	v_lshlrev_b32_e32 v90, 16, v170
	v_and_b32_e32 v91, 0xffff0000, v170
	v_lshlrev_b32_e32 v92, 16, v171
	v_and_b32_e32 v93, 0xffff0000, v171
	v_and_b32_e32 v95, 0xffff0000, v172
	v_lshlrev_b32_e32 v96, 16, v173
	v_and_b32_e32 v97, 0xffff0000, v173
	v_pk_fma_f32 v[88:89], v[88:89], 0.5, v[92:93] op_sel_hi:[1,0,1]
	v_pk_fma_f32 v[86:87], v[86:87], 0.5, v[90:91] op_sel_hi:[1,0,1]
	v_pk_fma_f32 v[78:79], v[78:79], 0.5, v[94:95] op_sel_hi:[1,0,1]
	v_pk_fma_f32 v[80:81], v[80:81], 0.5, v[96:97] op_sel_hi:[1,0,1]
	global_store_dwordx4 v[98:99], v[86:89], off offset:512
	global_store_dwordx4 v[98:99], v[78:81], off offset:528
	s_nop 0
	v_lshlrev_b32_e32 v86, 16, v168
	v_lshlrev_b32_e32 v78, 16, v166
	v_and_b32_e32 v79, 0xffff0000, v166
	v_pk_fma_f32 v[78:79], v[82:83], 0.5, v[78:79] op_sel_hi:[1,0,1]
	v_lshlrev_b64 v[82:83], 12, v[212:213]
	v_lshlrev_b32_e32 v80, 16, v167
	v_and_b32_e32 v81, 0xffff0000, v167
	v_and_b32_e32 v87, 0xffff0000, v168
	v_lshlrev_b32_e32 v88, 16, v169
	v_and_b32_e32 v89, 0xffff0000, v169
	v_lshl_add_u64 v[82:83], s[88:89], 0, v[82:83]
	v_pk_fma_f32 v[80:81], v[84:85], 0.5, v[80:81] op_sel_hi:[1,0,1]
	v_pk_fma_f32 v[76:77], v[76:77], 0.5, v[88:89] op_sel_hi:[1,0,1]
	v_pk_fma_f32 v[74:75], v[74:75], 0.5, v[86:87] op_sel_hi:[1,0,1]
	v_lshl_add_u64 v[82:83], v[82:83], 0, v[122:123]
	global_store_dwordx4 v[82:83], v[78:81], off
	global_store_dwordx4 v[82:83], v[74:77], off offset:16
	s_nop 0
	v_lshlrev_b32_e32 v78, 16, v164
	v_lshlrev_b32_e32 v74, 16, v162
	v_and_b32_e32 v75, 0xffff0000, v162
	v_lshlrev_b32_e32 v76, 16, v163
	v_and_b32_e32 v77, 0xffff0000, v163
	v_and_b32_e32 v79, 0xffff0000, v164
	v_lshlrev_b32_e32 v80, 16, v165
	v_and_b32_e32 v81, 0xffff0000, v165
	v_pk_fma_f32 v[72:73], v[72:73], 0.5, v[76:77] op_sel_hi:[1,0,1]
	v_pk_fma_f32 v[70:71], v[70:71], 0.5, v[74:75] op_sel_hi:[1,0,1]
	v_pk_fma_f32 v[66:67], v[66:67], 0.5, v[78:79] op_sel_hi:[1,0,1]
	v_pk_fma_f32 v[68:69], v[68:69], 0.5, v[80:81] op_sel_hi:[1,0,1]
	global_store_dwordx4 v[82:83], v[70:73], off offset:512
	global_store_dwordx4 v[82:83], v[66:69], off offset:528
	s_nop 0
	v_lshlrev_b32_e32 v70, 16, v160
	v_lshlrev_b32_e32 v66, 16, v158
	v_and_b32_e32 v67, 0xffff0000, v158
	v_pk_fma_f32 v[62:63], v[62:63], 0.5, v[66:67] op_sel_hi:[1,0,1]
	v_lshlrev_b64 v[66:67], 12, v[210:211]
	v_lshlrev_b32_e32 v68, 16, v159
	v_and_b32_e32 v69, 0xffff0000, v159
	v_and_b32_e32 v71, 0xffff0000, v160
	v_lshlrev_b32_e32 v72, 16, v161
	v_and_b32_e32 v73, 0xffff0000, v161
	v_lshl_add_u64 v[66:67], s[88:89], 0, v[66:67]
	v_pk_fma_f32 v[64:65], v[64:65], 0.5, v[68:69] op_sel_hi:[1,0,1]
	v_pk_fma_f32 v[60:61], v[60:61], 0.5, v[72:73] op_sel_hi:[1,0,1]
	v_pk_fma_f32 v[58:59], v[58:59], 0.5, v[70:71] op_sel_hi:[1,0,1]
	v_lshl_add_u64 v[66:67], v[66:67], 0, v[122:123]
	global_store_dwordx4 v[66:67], v[62:65], off
	global_store_dwordx4 v[66:67], v[58:61], off offset:16
	s_nop 0
	v_lshlrev_b32_e32 v62, 16, v156
	v_lshlrev_b32_e32 v58, 16, v154
	v_and_b32_e32 v59, 0xffff0000, v154
	v_lshlrev_b32_e32 v60, 16, v155
	v_and_b32_e32 v61, 0xffff0000, v155
	v_and_b32_e32 v63, 0xffff0000, v156
	v_lshlrev_b32_e32 v64, 16, v157
	v_and_b32_e32 v65, 0xffff0000, v157
	v_pk_fma_f32 v[56:57], v[56:57], 0.5, v[60:61] op_sel_hi:[1,0,1]
	v_pk_fma_f32 v[54:55], v[54:55], 0.5, v[58:59] op_sel_hi:[1,0,1]
	v_pk_fma_f32 v[46:47], v[46:47], 0.5, v[62:63] op_sel_hi:[1,0,1]
	v_pk_fma_f32 v[48:49], v[48:49], 0.5, v[64:65] op_sel_hi:[1,0,1]
	global_store_dwordx4 v[66:67], v[54:57], off offset:512
	global_store_dwordx4 v[66:67], v[46:49], off offset:528
	s_nop 0
	v_lshlrev_b32_e32 v54, 16, v152
	v_lshlrev_b32_e32 v46, 16, v150
;     __device__ __forceinline__ void operator()(const f32x4 (&acc)[2][2][4][2], const pg8::Unit& u, int wr, int wc, int fr, int fq) const {
;     ...
;             for (int ai = 0; ai < 2; ++ai)
; #pragma unroll
;                 for (int m = 0; m < 4; ++m) { float q = 0.f;
; #pragma unroll
;                     for (int bj = 0; bj < 2; ++bj) { const u32x4 t = w[ai][m][bj];
;                         const f32x4 b0 = {__uint_as_float(t.x << 16), __uint_as_float(t.x & 0xffff0000u), __uint_as_float(t.y << 16), __uint_as_float(t.y & 0xffff0000u)};
;                         const f32x4 b1 = {__uint_as_float(t.z << 16), __uint_as_float(t.z & 0xffff0000u), __uint_as_float(t.w << 16), __uint_as_float(t.w & 0xffff0000u)};
;                         q += emit(b0 + acc[ai][bj][m][0] * alpha, b1 + acc[ai][bj][m][1] * alpha, (size_t)(row0 + ai * 128 + m * 16) * DM + col0 + bj * 128); }
;     __device__ __forceinline__ float emit(const f32x4 v0, const f32x4 v1, size_t off) const {
;         if (MODE == 2) { *(f32x4*)(out + off) = v0; *(f32x4*)(out + off + 4) = v1; return 0.f; }
	v_and_b32_e32 v47, 0xffff0000, v150
	v_pk_fma_f32 v[46:47], v[50:51], 0.5, v[46:47] op_sel_hi:[1,0,1]
	v_lshlrev_b64 v[50:51], 12, v[208:209]
	v_lshlrev_b32_e32 v48, 16, v151
	v_and_b32_e32 v49, 0xffff0000, v151
	v_and_b32_e32 v55, 0xffff0000, v152
	v_lshlrev_b32_e32 v56, 16, v153
	v_and_b32_e32 v57, 0xffff0000, v153
	v_lshl_add_u64 v[50:51], s[88:89], 0, v[50:51]
	v_pk_fma_f32 v[48:49], v[52:53], 0.5, v[48:49] op_sel_hi:[1,0,1]
	v_pk_fma_f32 v[44:45], v[44:45], 0.5, v[56:57] op_sel_hi:[1,0,1]
	v_pk_fma_f32 v[42:43], v[42:43], 0.5, v[54:55] op_sel_hi:[1,0,1]
	v_lshl_add_u64 v[50:51], v[50:51], 0, v[122:123]
	global_store_dwordx4 v[50:51], v[46:49], off
	global_store_dwordx4 v[50:51], v[42:45], off offset:16
	s_nop 0
	v_lshlrev_b32_e32 v46, 16, v148
	v_lshlrev_b32_e32 v42, 16, v146
	v_and_b32_e32 v43, 0xffff0000, v146
	v_lshlrev_b32_e32 v44, 16, v147
	v_and_b32_e32 v45, 0xffff0000, v147
	v_and_b32_e32 v47, 0xffff0000, v148
	v_lshlrev_b32_e32 v48, 16, v149
	v_and_b32_e32 v49, 0xffff0000, v149
	v_pk_fma_f32 v[40:41], v[40:41], 0.5, v[44:45] op_sel_hi:[1,0,1]
	v_pk_fma_f32 v[38:39], v[38:39], 0.5, v[42:43] op_sel_hi:[1,0,1]
	v_pk_fma_f32 v[30:31], v[30:31], 0.5, v[46:47] op_sel_hi:[1,0,1]
	v_pk_fma_f32 v[32:33], v[32:33], 0.5, v[48:49] op_sel_hi:[1,0,1]
	global_store_dwordx4 v[50:51], v[38:41], off offset:512
	global_store_dwordx4 v[50:51], v[30:33], off offset:528
	s_nop 0
	v_lshlrev_b32_e32 v38, 16, v144
	v_lshlrev_b32_e32 v30, 16, v142
	v_and_b32_e32 v31, 0xffff0000, v142
	v_pk_fma_f32 v[30:31], v[34:35], 0.5, v[30:31] op_sel_hi:[1,0,1]
	v_lshlrev_b64 v[34:35], 12, v[206:207]
	v_lshlrev_b32_e32 v32, 16, v143
	v_and_b32_e32 v33, 0xffff0000, v143
	v_and_b32_e32 v39, 0xffff0000, v144
	v_lshlrev_b32_e32 v40, 16, v145
	v_and_b32_e32 v41, 0xffff0000, v145
	v_lshl_add_u64 v[34:35], s[88:89], 0, v[34:35]
	v_pk_fma_f32 v[32:33], v[36:37], 0.5, v[32:33] op_sel_hi:[1,0,1]
	v_pk_fma_f32 v[28:29], v[28:29], 0.5, v[40:41] op_sel_hi:[1,0,1]
	v_pk_fma_f32 v[26:27], v[26:27], 0.5, v[38:39] op_sel_hi:[1,0,1]
	v_lshl_add_u64 v[34:35], v[34:35], 0, v[122:123]
	global_store_dwordx4 v[34:35], v[30:33], off
	global_store_dwordx4 v[34:35], v[26:29], off offset:16
	s_nop 0
	v_lshlrev_b32_e32 v30, 16, v136
	v_lshlrev_b32_e32 v26, 16, v134
	v_and_b32_e32 v27, 0xffff0000, v134
	v_lshlrev_b32_e32 v28, 16, v135
	v_and_b32_e32 v29, 0xffff0000, v135
	v_and_b32_e32 v31, 0xffff0000, v136
	v_lshlrev_b32_e32 v32, 16, v137
	v_and_b32_e32 v33, 0xffff0000, v137
	v_pk_fma_f32 v[24:25], v[24:25], 0.5, v[28:29] op_sel_hi:[1,0,1]
	v_pk_fma_f32 v[22:23], v[22:23], 0.5, v[26:27] op_sel_hi:[1,0,1]
	v_pk_fma_f32 v[14:15], v[14:15], 0.5, v[30:31] op_sel_hi:[1,0,1]
	v_pk_fma_f32 v[16:17], v[16:17], 0.5, v[32:33] op_sel_hi:[1,0,1]
	global_store_dwordx4 v[34:35], v[22:25], off offset:512
	global_store_dwordx4 v[34:35], v[14:17], off offset:528
	s_nop 0
	v_lshlrev_b32_e32 v22, 16, v140
	v_lshlrev_b32_e32 v14, 16, v138
	v_and_b32_e32 v15, 0xffff0000, v138
	v_pk_fma_f32 v[14:15], v[18:19], 0.5, v[14:15] op_sel_hi:[1,0,1]
	v_lshlrev_b64 v[18:19], 12, v[204:205]
	v_lshlrev_b32_e32 v16, 16, v139
	v_and_b32_e32 v17, 0xffff0000, v139
	v_and_b32_e32 v23, 0xffff0000, v140
	v_lshlrev_b32_e32 v24, 16, v141
	v_and_b32_e32 v25, 0xffff0000, v141
	v_lshl_add_u64 v[18:19], s[88:89], 0, v[18:19]
	v_pk_fma_f32 v[16:17], v[20:21], 0.5, v[16:17] op_sel_hi:[1,0,1]
	v_pk_fma_f32 v[12:13], v[12:13], 0.5, v[24:25] op_sel_hi:[1,0,1]
	v_pk_fma_f32 v[10:11], v[10:11], 0.5, v[22:23] op_sel_hi:[1,0,1]
	v_lshl_add_u64 v[18:19], v[18:19], 0, v[122:123]
	global_store_dwordx4 v[18:19], v[14:17], off
	global_store_dwordx4 v[18:19], v[10:13], off offset:16
	s_nop 0
	v_lshlrev_b32_e32 v14, 16, v132
	v_lshlrev_b32_e32 v10, 16, v130
	v_and_b32_e32 v11, 0xffff0000, v130
	v_lshlrev_b32_e32 v12, 16, v131
	v_and_b32_e32 v13, 0xffff0000, v131
	v_and_b32_e32 v15, 0xffff0000, v132
	v_lshlrev_b32_e32 v16, 16, v133
	v_and_b32_e32 v17, 0xffff0000, v133
	v_pk_fma_f32 v[8:9], v[8:9], 0.5, v[12:13] op_sel_hi:[1,0,1]
	v_pk_fma_f32 v[6:7], v[6:7], 0.5, v[10:11] op_sel_hi:[1,0,1]
	v_pk_fma_f32 v[4:5], v[4:5], 0.5, v[16:17] op_sel_hi:[1,0,1]
	v_pk_fma_f32 v[2:3], v[2:3], 0.5, v[14:15] op_sel_hi:[1,0,1]
	global_store_dwordx4 v[18:19], v[6:9], off offset:512
	global_store_dwordx4 v[18:19], v[2:5], off offset:528
	s_cbranch_vccnz .LBB0_441
	s_andn2_b64 vcc, exec, s[44:45]
	s_cbranch_vccnz .LBB0_440
	s_barrier
	s_branch .LBB0_440
